# grid-barrier poll loops: s_sleep 1 back-off replaced by s_nop 0 (same code size), on top of ring peel
# baseline (speedup 1.0000x reference)
; __global__ void __launch_bounds__(NTHREADS) mega_fwd(P p) {
;     ...
;     if (p.ws == nullptr) grid.sync();
.LBB0_36:
	s_nop 0
	global_load_dword v2, v0, s[2:3] offset:32 sc1
	s_waitcnt vmcnt(0)
	v_and_b32_e32 v2, 0xffff0000, v2
	v_cmp_ne_u32_e32 vcc, v2, v1
	s_or_b64 s[10:11], vcc, s[10:11]
	s_andn2_b64 exec, exec, s[10:11]
	s_cbranch_execnz .LBB0_36

; __device__ __forceinline__ unsigned xb_ld(unsigned* p)              { return __hip_atomic_load(p, __ATOMIC_RELAXED, __HIP_MEMORY_SCOPE_AGENT); }
; __device__ __forceinline__ void xcd_barrier_complete(unsigned* bar, unsigned x, unsigned& nloc, unsigned& nx) {
;     const unsigned G = gridDim.x * gridDim.y * gridDim.z;
;     unsigned sum, cnt, mine, sp = 0u;
;     for (;;) {
;         sum = 0u; cnt = 0u; mine = 0u;
; #pragma unroll
;         for (unsigned j = 0; j < 16; ++j) { const unsigned c = xb_ld(&bar[XB_XCNT(j)]); sum += c; cnt += (c > 0u) ? 1u : 0u; mine = (j == x) ? c : mine; }
;         if (sum == G) break;
;         __builtin_amdgcn_s_sleep(1);
;         if ((++sp & 255u) == 0u) { if (xb_ld(&bar[XB_TMO])) break; if (sp > XB_SPIN_CAP) { atomicAdd(&bar[XB_TMO], 1u); break; } }
;     }
;     nloc = mine > 0u ? mine : 1u; nx = cnt > 0u ? cnt : 1u;
; }
.LBB0_45:
	global_load_dword v15, v16, s[36:37] offset:1024 sc1
	s_waitcnt lgkmcnt(0)
	global_load_dword v0, v16, s[36:37] offset:1280 sc1
	global_load_dword v1, v16, s[36:37] offset:1536 sc1
	global_load_dword v2, v16, s[36:37] offset:1792 sc1
	global_load_dword v3, v16, s[36:37] offset:2048 sc1
	global_load_dword v4, v16, s[36:37] offset:2304 sc1
	global_load_dword v5, v16, s[36:37] offset:2560 sc1
	global_load_dword v6, v16, s[36:37] offset:2816 sc1
	global_load_dword v7, v16, s[36:37] offset:3072 sc1
	global_load_dword v8, v16, s[36:37] offset:3328 sc1
	global_load_dword v9, v16, s[36:37] offset:3584 sc1
	global_load_dword v10, v16, s[36:37] offset:3840 sc1
	global_load_dword v11, v16, s[6:7] sc1
	global_load_dword v12, v16, s[8:9] sc1
	global_load_dword v13, v16, s[10:11] sc1
	global_load_dword v14, v16, s[12:13] sc1
	s_mov_b64 s[14:15], -1
	s_mov_b64 s[16:17], -1
	s_waitcnt vmcnt(14)
	v_add_u32_e32 v17, v0, v15
	s_waitcnt vmcnt(13)
	v_add_u32_e32 v17, v17, v1
	s_waitcnt vmcnt(12)
	v_add_u32_e32 v17, v17, v2
	s_waitcnt vmcnt(11)
	v_add_u32_e32 v17, v17, v3
	s_waitcnt vmcnt(10)
	v_add_u32_e32 v17, v17, v4
	s_waitcnt vmcnt(9)
	v_add_u32_e32 v17, v17, v5
	s_waitcnt vmcnt(8)
	v_add_u32_e32 v17, v17, v6
	s_waitcnt vmcnt(7)
	v_add_u32_e32 v17, v17, v7
	s_waitcnt vmcnt(6)
	v_add_u32_e32 v17, v17, v8
	s_waitcnt vmcnt(5)
	v_add_u32_e32 v17, v17, v9
	s_waitcnt vmcnt(4)
	v_add_u32_e32 v17, v17, v10
	s_waitcnt vmcnt(3)
	v_add_u32_e32 v17, v17, v11
	s_waitcnt vmcnt(2)
	v_add_u32_e32 v17, v17, v12
	s_waitcnt vmcnt(1)
	v_add_u32_e32 v17, v17, v13
	s_waitcnt vmcnt(0)
	v_add_u32_e32 v17, v17, v14
	v_cmp_eq_u32_e32 vcc, s5, v17
	s_cbranch_vccnz .LBB0_44
	s_and_b32 s14, s20, 0xff
	s_cmp_eq_u32 s14, 0
	s_mov_b64 s[14:15], -1
	s_mov_b64 s[18:19], -1
	s_nop 0
	s_cbranch_scc1 .LBB0_49
	s_and_b64 vcc, exec, s[18:19]
	s_cbranch_vccz .LBB0_44

; __device__ __forceinline__ unsigned xb_ld(unsigned* p)              { return __hip_atomic_load(p, __ATOMIC_RELAXED, __HIP_MEMORY_SCOPE_AGENT); }
; __device__ __forceinline__ unsigned xb_add(unsigned* p, unsigned v) { return __hip_atomic_fetch_add(p, v, __ATOMIC_RELAXED, __HIP_MEMORY_SCOPE_AGENT); }
; #define XB_SPIN(cond, bar) do { unsigned _sp = 0; while (cond) { __builtin_amdgcn_s_sleep(1); \
;     if ((++_sp & 255u) == 0u) { if (xb_ld(&(bar)[XB_TMO])) break; if (_sp > XB_SPIN_CAP) { atomicAdd(&(bar)[XB_TMO], 1u); break; } } } } while (0)
; __device__ __forceinline__ void xcd_barrier(const XcdBarrier& b) {
;     ...
;             else XB_SPIN(xb_ld(&bar[XB_TOPGEN]) == tg, bar);
;             __builtin_amdgcn_fence(__ATOMIC_ACQUIRE, "agent");
;             xb_add(&bar[XB_XGEN(b.x)], 1u);
;             asm volatile("s_waitcnt vmcnt(0)" ::: "memory");
;         } else {
;             XB_SPIN(xb_ld(&bar[XB_XGEN(b.x)]) == gen, bar);
.LBB0_63:
	s_and_b32 s22, s5, 0xff
	s_mov_b64 s[20:21], -1
	s_cmp_lg_u32 s22, 0
	s_mov_b64 s[24:25], -1
	s_nop 0
	s_cbranch_scc0 .LBB0_66
	s_and_b64 vcc, exec, s[24:25]
	s_cbranch_vccz .LBB0_62

; __device__ __forceinline__ unsigned xb_ld(unsigned* p)              { return __hip_atomic_load(p, __ATOMIC_RELAXED, __HIP_MEMORY_SCOPE_AGENT); }
; __device__ __forceinline__ unsigned xb_add(unsigned* p, unsigned v) { return __hip_atomic_fetch_add(p, v, __ATOMIC_RELAXED, __HIP_MEMORY_SCOPE_AGENT); }
; #define XB_SPIN(cond, bar) do { unsigned _sp = 0; while (cond) { __builtin_amdgcn_s_sleep(1); \
;     if ((++_sp & 255u) == 0u) { if (xb_ld(&(bar)[XB_TMO])) break; if (_sp > XB_SPIN_CAP) { atomicAdd(&(bar)[XB_TMO], 1u); break; } } } } while (0)
; __device__ __forceinline__ void xcd_barrier(const XcdBarrier& b) {
;     ...
;             else XB_SPIN(xb_ld(&bar[XB_TOPGEN]) == tg, bar);
;             __builtin_amdgcn_fence(__ATOMIC_ACQUIRE, "agent");
;             xb_add(&bar[XB_XGEN(b.x)], 1u);
;             asm volatile("s_waitcnt vmcnt(0)" ::: "memory");
;         } else {
;             XB_SPIN(xb_ld(&bar[XB_XGEN(b.x)]) == gen, bar);
.LBB0_80:
	s_and_b32 s24, s5, 0xff
	s_cmp_lg_u32 s24, 0
	s_mov_b64 s[26:27], -1
	s_nop 0
	s_cbranch_scc0 .LBB0_83
	s_mov_b64 s[28:29], -1
	s_and_b64 vcc, exec, s[26:27]
	s_cbranch_vccz .LBB0_79

; __device__ __forceinline__ unsigned xb_ld(unsigned* p)              { return __hip_atomic_load(p, __ATOMIC_RELAXED, __HIP_MEMORY_SCOPE_AGENT); }
; __device__ __forceinline__ void xcd_barrier_complete(unsigned* bar, unsigned x, unsigned& nloc, unsigned& nx) {
;     const unsigned G = gridDim.x * gridDim.y * gridDim.z;
;     unsigned sum, cnt, mine, sp = 0u;
;     for (;;) {
;         sum = 0u; cnt = 0u; mine = 0u;
; #pragma unroll
;         for (unsigned j = 0; j < 16; ++j) { const unsigned c = xb_ld(&bar[XB_XCNT(j)]); sum += c; cnt += (c > 0u) ? 1u : 0u; mine = (j == x) ? c : mine; }
;         if (sum == G) break;
;         __builtin_amdgcn_s_sleep(1);
;         if ((++sp & 255u) == 0u) { if (xb_ld(&bar[XB_TMO])) break; if (sp > XB_SPIN_CAP) { atomicAdd(&bar[XB_TMO], 1u); break; } }
;     }
;     nloc = mine > 0u ? mine : 1u; nx = cnt > 0u ? cnt : 1u;
; }
.LBB0_108:
	v_readlane_b32 s6, v253, 11
	v_readlane_b32 s7, v253, 12
	global_load_dword v12, v1, s[36:37] offset:1024 sc1
	global_load_dword v0, v1, s[36:37] offset:1280 sc1
	s_waitcnt lgkmcnt(0)
	global_load_dword v2, v1, s[36:37] offset:1536 sc1
	global_load_dword v3, v1, s[36:37] offset:1792 sc1
	global_load_dword v4, v1, s[36:37] offset:2048 sc1
	global_load_dword v5, v1, s[36:37] offset:2304 sc1
	global_load_dword v6, v1, s[36:37] offset:2560 sc1
	global_load_dword v7, v1, s[36:37] offset:2816 sc1
	global_load_dword v8, v1, s[36:37] offset:3072 sc1
	global_load_dword v9, v1, s[36:37] offset:3328 sc1
	global_load_dword v10, v1, s[36:37] offset:3584 sc1
	global_load_dword v11, v1, s[36:37] offset:3840 sc1
	global_load_dword v13, v1, s[6:7] sc1
	v_readlane_b32 s6, v253, 13
	v_readlane_b32 s7, v253, 14
	v_readlane_b32 s8, v253, 8
	s_waitcnt vmcnt(11)
	v_add_u32_e32 v17, v0, v12
	s_nop 1
	global_load_dword v14, v1, s[6:7] sc1
	v_readlane_b32 s6, v253, 15
	v_readlane_b32 s7, v253, 16
	s_waitcnt vmcnt(11)
	v_add_u32_e32 v17, v17, v2
	s_waitcnt vmcnt(10)
	v_add_u32_e32 v17, v17, v3
	s_waitcnt vmcnt(9)
	v_add_u32_e32 v17, v17, v4
	s_waitcnt vmcnt(8)
	v_add_u32_e32 v17, v17, v5
	s_waitcnt vmcnt(7)
	v_add_u32_e32 v17, v17, v6
	global_load_dword v15, v1, s[6:7] sc1
	v_readlane_b32 s6, v253, 17
	v_readlane_b32 s7, v253, 18
	s_waitcnt vmcnt(7)
	v_add_u32_e32 v17, v17, v7
	s_waitcnt vmcnt(6)
	v_add_u32_e32 v17, v17, v8
	s_waitcnt vmcnt(5)
	v_add_u32_e32 v17, v17, v9
	s_waitcnt vmcnt(4)
	v_add_u32_e32 v17, v17, v10
	s_waitcnt vmcnt(3)
	v_add_u32_e32 v17, v17, v11
	global_load_dword v16, v1, s[6:7] sc1
	s_waitcnt vmcnt(3)
	v_add_u32_e32 v17, v17, v13
	s_mov_b64 s[6:7], -1
	s_waitcnt vmcnt(2)
	v_add_u32_e32 v17, v17, v14
	s_waitcnt vmcnt(1)
	v_add_u32_e32 v17, v17, v15
	s_waitcnt vmcnt(0)
	v_add_u32_e32 v17, v17, v16
	v_cmp_eq_u32_e32 vcc, s8, v17
	s_mov_b64 s[8:9], -1
	s_cbranch_vccnz .LBB0_107
	s_and_b32 s6, s12, 0xff
	s_cmp_eq_u32 s6, 0
	s_mov_b64 s[6:7], -1
	s_mov_b64 s[10:11], -1
	s_nop 0
	s_cbranch_scc1 .LBB0_112
	s_and_b64 vcc, exec, s[10:11]
	s_cbranch_vccz .LBB0_107

; __device__ __forceinline__ unsigned xb_ld(unsigned* p)              { return __hip_atomic_load(p, __ATOMIC_RELAXED, __HIP_MEMORY_SCOPE_AGENT); }
; __device__ __forceinline__ unsigned xb_add(unsigned* p, unsigned v) { return __hip_atomic_fetch_add(p, v, __ATOMIC_RELAXED, __HIP_MEMORY_SCOPE_AGENT); }
; #define XB_SPIN(cond, bar) do { unsigned _sp = 0; while (cond) { __builtin_amdgcn_s_sleep(1); \
;     if ((++_sp & 255u) == 0u) { if (xb_ld(&(bar)[XB_TMO])) break; if (_sp > XB_SPIN_CAP) { atomicAdd(&(bar)[XB_TMO], 1u); break; } } } } while (0)
; __device__ __forceinline__ void xcd_barrier(const XcdBarrier& b) {
;     ...
;             else XB_SPIN(xb_ld(&bar[XB_TOPGEN]) == tg, bar);
;             __builtin_amdgcn_fence(__ATOMIC_ACQUIRE, "agent");
;             xb_add(&bar[XB_XGEN(b.x)], 1u);
;             asm volatile("s_waitcnt vmcnt(0)" ::: "memory");
;         } else {
;             XB_SPIN(xb_ld(&bar[XB_XGEN(b.x)]) == gen, bar);
.LBB0_124:
	s_and_b32 s16, s20, 0xff
	s_mov_b64 s[14:15], -1
	s_cmp_lg_u32 s16, 0
	s_mov_b64 s[18:19], -1
	s_nop 0
	s_cbranch_scc0 .LBB0_127
	s_and_b64 vcc, exec, s[18:19]
	s_cbranch_vccz .LBB0_123

; __device__ __forceinline__ unsigned xb_ld(unsigned* p)              { return __hip_atomic_load(p, __ATOMIC_RELAXED, __HIP_MEMORY_SCOPE_AGENT); }
; __device__ __forceinline__ unsigned xb_add(unsigned* p, unsigned v) { return __hip_atomic_fetch_add(p, v, __ATOMIC_RELAXED, __HIP_MEMORY_SCOPE_AGENT); }
; #define XB_SPIN(cond, bar) do { unsigned _sp = 0; while (cond) { __builtin_amdgcn_s_sleep(1); \
;     if ((++_sp & 255u) == 0u) { if (xb_ld(&(bar)[XB_TMO])) break; if (_sp > XB_SPIN_CAP) { atomicAdd(&(bar)[XB_TMO], 1u); break; } } } } while (0)
; __device__ __forceinline__ void xcd_barrier(const XcdBarrier& b) {
;     ...
;             else XB_SPIN(xb_ld(&bar[XB_TOPGEN]) == tg, bar);
;             __builtin_amdgcn_fence(__ATOMIC_ACQUIRE, "agent");
;             xb_add(&bar[XB_XGEN(b.x)], 1u);
;             asm volatile("s_waitcnt vmcnt(0)" ::: "memory");
;         } else {
;             XB_SPIN(xb_ld(&bar[XB_XGEN(b.x)]) == gen, bar);
.LBB0_141:
	s_and_b32 s18, s22, 0xff
	s_mov_b64 s[16:17], -1
	s_cmp_lg_u32 s18, 0
	s_mov_b64 s[20:21], -1
	s_nop 0
	s_cbranch_scc0 .LBB0_144
	s_and_b64 vcc, exec, s[20:21]
	s_cbranch_vccz .LBB0_140

; __device__ __forceinline__ unsigned xb_ld(unsigned* p)              { return __hip_atomic_load(p, __ATOMIC_RELAXED, __HIP_MEMORY_SCOPE_AGENT); }
; __device__ __forceinline__ void xcd_barrier_complete(unsigned* bar, unsigned x, unsigned& nloc, unsigned& nx) {
;     const unsigned G = gridDim.x * gridDim.y * gridDim.z;
;     unsigned sum, cnt, mine, sp = 0u;
;     for (;;) {
;         sum = 0u; cnt = 0u; mine = 0u;
; #pragma unroll
;         for (unsigned j = 0; j < 16; ++j) { const unsigned c = xb_ld(&bar[XB_XCNT(j)]); sum += c; cnt += (c > 0u) ? 1u : 0u; mine = (j == x) ? c : mine; }
;         if (sum == G) break;
;         __builtin_amdgcn_s_sleep(1);
;         if ((++sp & 255u) == 0u) { if (xb_ld(&bar[XB_TMO])) break; if (sp > XB_SPIN_CAP) { atomicAdd(&bar[XB_TMO], 1u); break; } }
;     }
;     nloc = mine > 0u ? mine : 1u; nx = cnt > 0u ? cnt : 1u;
; }
.LBB0_792:
	v_readlane_b32 s12, v253, 11
	v_readlane_b32 s13, v253, 12
	global_load_dword v12, v1, s[36:37] offset:1024 sc1
	global_load_dword v0, v1, s[36:37] offset:1280 sc1
	s_waitcnt lgkmcnt(0)
	global_load_dword v2, v1, s[36:37] offset:1536 sc1
	global_load_dword v3, v1, s[36:37] offset:1792 sc1
	global_load_dword v4, v1, s[36:37] offset:2048 sc1
	global_load_dword v5, v1, s[36:37] offset:2304 sc1
	global_load_dword v6, v1, s[36:37] offset:2560 sc1
	global_load_dword v7, v1, s[36:37] offset:2816 sc1
	global_load_dword v8, v1, s[36:37] offset:3072 sc1
	global_load_dword v9, v1, s[36:37] offset:3328 sc1
	global_load_dword v10, v1, s[36:37] offset:3584 sc1
	global_load_dword v11, v1, s[36:37] offset:3840 sc1
	global_load_dword v13, v1, s[12:13] sc1
	v_readlane_b32 s12, v253, 13
	v_readlane_b32 s13, v253, 14
	v_readlane_b32 s14, v253, 8
	s_waitcnt vmcnt(11)
	v_add_u32_e32 v17, v0, v12
	s_nop 1
	global_load_dword v14, v1, s[12:13] sc1
	v_readlane_b32 s12, v253, 15
	v_readlane_b32 s13, v253, 16
	s_waitcnt vmcnt(11)
	v_add_u32_e32 v17, v17, v2
	s_waitcnt vmcnt(10)
	v_add_u32_e32 v17, v17, v3
	s_waitcnt vmcnt(9)
	v_add_u32_e32 v17, v17, v4
	s_waitcnt vmcnt(8)
	v_add_u32_e32 v17, v17, v5
	s_waitcnt vmcnt(7)
	v_add_u32_e32 v17, v17, v6
	global_load_dword v15, v1, s[12:13] sc1
	v_readlane_b32 s12, v253, 17
	v_readlane_b32 s13, v253, 18
	s_waitcnt vmcnt(7)
	v_add_u32_e32 v17, v17, v7
	s_waitcnt vmcnt(6)
	v_add_u32_e32 v17, v17, v8
	s_waitcnt vmcnt(5)
	v_add_u32_e32 v17, v17, v9
	s_waitcnt vmcnt(4)
	v_add_u32_e32 v17, v17, v10
	s_waitcnt vmcnt(3)
	v_add_u32_e32 v17, v17, v11
	global_load_dword v16, v1, s[12:13] sc1
	s_waitcnt vmcnt(3)
	v_add_u32_e32 v17, v17, v13
	s_mov_b64 s[12:13], -1
	s_waitcnt vmcnt(2)
	v_add_u32_e32 v17, v17, v14
	s_waitcnt vmcnt(1)
	v_add_u32_e32 v17, v17, v15
	s_waitcnt vmcnt(0)
	v_add_u32_e32 v17, v17, v16
	v_cmp_eq_u32_e32 vcc, s14, v17
	s_mov_b64 s[14:15], -1
	s_cbranch_vccnz .LBB0_791
	s_and_b32 s12, s18, 0xff
	s_cmp_eq_u32 s12, 0
	s_mov_b64 s[12:13], -1
	s_mov_b64 s[16:17], -1
	s_nop 0
	s_cbranch_scc1 .LBB0_796
	s_and_b64 vcc, exec, s[16:17]
	s_cbranch_vccz .LBB0_791

; __device__ __forceinline__ unsigned xb_ld(unsigned* p)              { return __hip_atomic_load(p, __ATOMIC_RELAXED, __HIP_MEMORY_SCOPE_AGENT); }
; __device__ __forceinline__ unsigned xb_add(unsigned* p, unsigned v) { return __hip_atomic_fetch_add(p, v, __ATOMIC_RELAXED, __HIP_MEMORY_SCOPE_AGENT); }
; #define XB_SPIN(cond, bar) do { unsigned _sp = 0; while (cond) { __builtin_amdgcn_s_sleep(1); \
;     if ((++_sp & 255u) == 0u) { if (xb_ld(&(bar)[XB_TMO])) break; if (_sp > XB_SPIN_CAP) { atomicAdd(&(bar)[XB_TMO], 1u); break; } } } } while (0)
; __device__ __forceinline__ void xcd_barrier(const XcdBarrier& b) {
;     ...
;             else XB_SPIN(xb_ld(&bar[XB_TOPGEN]) == tg, bar);
;             __builtin_amdgcn_fence(__ATOMIC_ACQUIRE, "agent");
;             xb_add(&bar[XB_XGEN(b.x)], 1u);
;             asm volatile("s_waitcnt vmcnt(0)" ::: "memory");
;         } else {
;             XB_SPIN(xb_ld(&bar[XB_XGEN(b.x)]) == gen, bar);
.LBB0_808:
	s_and_b32 s22, s26, 0xff
	s_mov_b64 s[20:21], -1
	s_cmp_lg_u32 s22, 0
	s_mov_b64 s[24:25], -1
	s_nop 0
	s_cbranch_scc0 .LBB0_811
	s_and_b64 vcc, exec, s[24:25]
	s_cbranch_vccz .LBB0_807
